# bundle: batched kernarg s_loads (attention front block, table stage 1), gain dwords fetched together, P2 skinny loads issued together
# baseline (speedup 1.0000x reference)
;     __device__ __forceinline__ Pre load(int row, int cl) const { const unsigned char* gp = (const unsigned char*)GSA + (size_t)row * 2048 + 1024 + cl; return Pre{__builtin_nontemporal_load((const u32x2*)gp), __builtin_nontemporal_load((const u32x2*)(gp + 32))}; }
;     __device__ __forceinline__ Pre load(int row, int cl) const { const bf16* hp = XB + (size_t)row * 1024 + cl; return Pre{__builtin_nontemporal_load((const u32x4*)hp), __builtin_nontemporal_load((const u32x4*)(hp + 32))}; }
; template <class F> __device__ __forceinline__ void skinny_task(const bf16* A16, int lda, const bf16* Bt, int ldb, int K, int pn, int wc, int lane, int wave, LAS float* red, int rowbase, int clbase, const F& f) {
;     ...
;     typename F::Pre pre = f.load(rowbase + fr, clbase + 8 * fq);
;     f32x4 c00 = {0.f, 0.f, 0.f, 0.f}, c01 = c00, c10 = c00, c11 = c00;
;     const bf16* tb = Bt + (size_t)(pn * 256 + 32 * wc) * ldb + fq * 8;
;     const bf16* b00 = tb + (size_t)pg8::perm32(fr) * ldb; const bf16* b01 = tb + (size_t)pg8::perm32(16 + fr) * ldb;
;     const bf16* b10 = b00 + (size_t)128 * ldb; const bf16* b11 = b01 + (size_t)128 * ldb;
;     const bf16* ap = A16 + (size_t)fr * lda + fq * 8;
; #pragma unroll 4
;     for (int k0 = 32 * wave; k0 < K; k0 += 256) {
;         const bf16x8 a = *(const bf16x8*)(ap + k0);
;         const bf16x8 v00 = *(const bf16x8*)(b00 + k0), v01 = *(const bf16x8*)(b01 + k0), v10 = *(const bf16x8*)(b10 + k0), v11 = *(const bf16x8*)(b11 + k0);
;         c00 = __builtin_amdgcn_mfma_f32_16x16x32_bf16(v00, a, c00, 0, 0, 0); c01 = __builtin_amdgcn_mfma_f32_16x16x32_bf16(v01, a, c01, 0, 0, 0);
;         c10 = __builtin_amdgcn_mfma_f32_16x16x32_bf16(v10, a, c10, 0, 0, 0); c11 = __builtin_amdgcn_mfma_f32_16x16x32_bf16(v11, a, c11, 0, 0, 0);
; template <class F> __device__ __forceinline__ void skinny_ssm(const bf16* UMp, const bf16* Bt, int ldb, int K, int bx, int G, int lane, int wave, LAS float* red, const F& f) {
;     ...
;     for (int t = bx; t < NG * 4; t += G) { const int g = t >> 2, wc = t & 3;
;         skinny_task(UMp + (size_t)(g * NCP + 2048) * UMK, UMK, Bt + (size_t)g * 256 * ldb, ldb, K, 0, wc, lane, wave, red, g * NCP + 2048, g * 256 + 64 * wc, f); }
.LBB0_404:
	s_ashr_i32 s12, s20, 2
	s_mul_i32 s21, s12, 0x900
	s_and_b32 s22, s20, 3
	s_addk_i32 s21, 0x800
	s_and_b64 vcc, exec, s[8:9]
	v_mov_b32_e32 v14, 0
	v_mov_b32_e32 v15, 0
	v_mov_b32_e32 v16, 0
	v_mov_b32_e32 v17, 0
	v_mov_b32_e32 v10, 0
	v_mov_b32_e32 v11, 0
	v_mov_b32_e32 v12, 0
	v_mov_b32_e32 v13, 0
	v_mov_b32_e32 v6, 0
	v_mov_b32_e32 v7, 0
	v_mov_b32_e32 v8, 0
	v_mov_b32_e32 v9, 0
	v_mov_b32_e32 v2, 0
	v_mov_b32_e32 v3, 0
	v_mov_b32_e32 v4, 0
	v_mov_b32_e32 v5, 0
	s_cbranch_vccz .LBB0_406
	s_ashr_i32 s13, s12, 31
	s_lshl_b64 s[12:13], s[12:13], 17
	s_add_u32 s12, s14, s12
	s_addc_u32 s13, s15, s13
	s_lshl_b32 s23, s22, 14
	s_add_u32 s12, s12, s23
	s_addc_u32 s13, s13, 0
	v_lshl_add_u64 v[2:3], v[18:19], 1, s[12:13]
	v_lshl_add_u64 v[2:3], v[2:3], 0, v[20:21]
	v_lshl_add_u64 v[10:11], v[2:3], 0, s[6:7]
	v_add_co_u32_e32 v28, vcc, s16, v10
	v_mad_i64_i32 v[12:13], s[12:13], s21, v26, v[22:23]
	s_nop 0
	v_addc_co_u32_e32 v29, vcc, 0, v11, vcc
	global_load_dwordx4 v[2:5], v[10:11], off
	global_load_dwordx4 v[14:17], v[12:13], off
	global_load_dwordx4 v[6:9], v[10:11], off offset:2048
	global_load_dwordx4 v[10:13], v[28:29], off
	s_nop 0
	global_load_dwordx4 v[28:31], v[28:29], off offset:2048
	s_waitcnt vmcnt(2)
	v_mfma_f32_16x16x32_bf16 v[6:9], v[6:9], v[14:17], 0
	v_mfma_f32_16x16x32_bf16 v[2:5], v[2:5], v[14:17], 0
	s_waitcnt vmcnt(1)
	v_mfma_f32_16x16x32_bf16 v[10:13], v[10:13], v[14:17], 0
	s_waitcnt vmcnt(0)
	v_mfma_f32_16x16x32_bf16 v[14:17], v[28:31], v[14:17], 0
